# nsa_main cross-loop prefetch: the window loop's first LDS-DMA tile group and its scalar address chain hoisted from the end of the selected-branch epilogue to its start (overlaps the epilogue), on top
# speedup vs baseline: 1.0010x; 1.0010x over previous
; __device__ __forceinline__ float bf2f(bf16 v) { return __uint_as_float(((unsigned)v) << 16); }
; __device__ __forceinline__ float sigmoidf_(float x) { return 1.0f / (1.0f + __expf(-x)); }
; #define LAS __attribute__((address_space(3)))
; #define LAS __attribute__((address_space(3)))
; template <int MODE> __device__ __forceinline__ void attn_branch(const bf16* __restrict__ Kbase, const bf16* __restrict__ VTbase, int kt_lo, int kt_hi, int tq0, int t, int h, int q, int tid, int wave, ...
;     ...
;     auto dma = [&](int kt, int buf) {
;         const char* kg = (const char*)Kbase + (size_t)kt * (64 * 128 * 2); const char* vg = (const char*)VTbase + kt * 128;
; #pragma unroll
;         for (int i = 0; i < 2; ++i) { const int n = 2 * wave + i;
;             __builtin_amdgcn_global_load_lds((const unsigned*)(kg + ((n >> 3) * 8192 + (n & 7) * 32) + kvo), (LAS unsigned*)(ldsl + buf * ATT_BUF + n * 1024), 16, 0, 0);
;             __builtin_amdgcn_global_load_lds((const unsigned*)(vg + ((size_t)(n >> 2) * (32 * SEQ * 2) + (n & 3) * 32) + vvo), (LAS unsigned*)(ldsl + buf * ATT_BUF + 16384 + n * 1024), 16, 0, 0); } };
;     const int lane16 = (h * 32 + q) * 16;
;     const int tlane = ATT_BTAB + ((0 - q) & 3) * (ATT_NEXT * 4) + 4 * (ATT_EOFF - ((0 - q) & 3));
;     ATT_BAR();
;     dma(kt_lo, 0);
;     if (kt_lo < kt_hi) { dma(kt_lo + 1, 1); asm volatile("s_waitcnt vmcnt(4)" ::: "memory"); } else asm volatile("s_waitcnt vmcnt(0)" ::: "memory");
; __device__ __forceinline__ void ph_nsa_main(const bf16* __restrict__ NQ, const bf16* __restrict__ KS, const bf16* __restrict__ KW, const bf16* __restrict__ VST, const bf16* __restrict__ VWT, ...
;     ...
;         { const float l = lsum + __shfl_xor(lsum, 32); const float sc = sigmoidf_(small[m * 32 + SM_GC + 6 + head]) / l;
; #pragma unroll
;           for (int dt = 0; dt < 4; ++dt)
; #pragma unroll
;               for (int gq = 0; gq < 4; ++gq) { const int d = 32 * dt + 8 * gq + 4 * h;
;                   const u32x2 ocv = *(const u32x2*)(mix + m * D_MODEL + 1280 + head * 128 + d);
;                   u32x2 w; w.x = cvt2(O[dt][4 * gq] * sc + bf2f((bf16)(ocv.x & 0xffff)), O[dt][4 * gq + 1] * sc + bf2f((bf16)(ocv.x >> 16)));
;                   w.y = cvt2(O[dt][4 * gq + 2] * sc + bf2f((bf16)(ocv.y & 0xffff)), O[dt][4 * gq + 3] * sc + bf2f((bf16)(ocv.y >> 16)));
;                   *(u32x2*)(mix + m * D_MODEL + 1280 + head * 128 + d) = w; }
.LBB0_1847:
	v_lshlrev_b64 v[68:69], 7, v[120:121]
	v_lshl_add_u64 v[68:69], s[6:7], 0, v[68:69]
	v_lshl_add_u64 v[190:191], s[16:17], 2, v[68:69]
	v_lshlrev_b64 v[68:69], 12, v[120:121]
	global_load_dword v102, v[190:191], off offset:72
	v_lshl_add_u64 v[68:69], s[0:1], 0, v[68:69]
	v_lshl_add_u64 v[68:69], s[18:19], 1, v[68:69]
	v_lshlrev_b32_e32 v70, 3, v179
	v_mov_b32_e32 v71, v3
	v_lshl_add_u64 v[70:71], v[68:69], 0, v[70:71]
	v_add_co_u32_e32 v68, vcc, s72, v70
	s_mov_b64 s[16:17], 0x6400a00
	s_nop 0
	v_addc_co_u32_e32 v69, vcc, 0, v71, vcc
	global_load_dwordx2 v[72:73], v[68:69], off offset:2560
	v_lshl_add_u64 v[186:187], v[70:71], 0, s[16:17]
	s_mov_b32 m0, s70
	s_add_i32 s16, s94, 0xfffffe00
	s_ashr_i32 s16, s16, 6
	s_cmpk_lt_i32 s75, 0x270
	s_cselect_b32 s16, s16, 0
	s_lshl_b64 s[14:15], s[14:15], 1
	s_add_u32 s34, s29, s14
	s_addc_u32 s35, s38, s15
	s_add_u32 s21, s42, s14
	s_addc_u32 s26, s43, s15
	s_ashr_i32 s17, s16, 31
	s_lshl_b64 s[14:15], s[16:17], 14
	s_add_u32 s17, s34, s14
	s_addc_u32 s31, s35, s15
	s_lshl_b32 s36, s16, 7
	s_ashr_i32 s18, s36, 31
	s_add_u32 s37, s21, s36
	s_addc_u32 s67, s26, s18
	s_add_u32 s18, s17, s64
	s_addc_u32 s19, s31, s76
	s_add_u32 s37, s37, s12
	s_addc_u32 s67, s67, s13
	v_lshl_add_u64 v[164:165], s[18:19], 0, v[2:3]
	s_add_u32 s18, s37, s55
	s_addc_u32 s19, s67, 0
	global_load_lds_dwordx4 v[164:165], off
	v_lshl_add_u64 v[164:165], s[18:19], 0, v[188:189]
	s_add_u32 s18, s17, s95
	s_mov_b32 m0, s90
	s_addc_u32 s19, s31, s96
	global_load_lds_dwordx4 v[164:165], off
	v_lshl_add_u64 v[164:165], s[18:19], 0, v[2:3]
	s_add_u32 s18, s37, s57
	s_mov_b32 m0, s97
	s_addc_u32 s19, s67, 0
	global_load_lds_dwordx4 v[164:165], off
	v_lshl_add_u64 v[164:165], s[18:19], 0, v[188:189]
	s_mov_b32 m0, s27
	s_nop 0
	global_load_lds_dwordx4 v[164:165], off
	global_load_dwordx2 v[76:77], v[186:187], off offset:16
	global_load_dwordx2 v[80:81], v[186:187], off offset:32
	global_load_dwordx2 v[86:87], v[186:187], off offset:48
	global_load_dwordx2 v[90:91], v[186:187], off offset:64
	global_load_dwordx2 v[70:71], v[186:187], off offset:80
	v_and_b32_e32 v75, 64, v234
	v_xor_b32_e32 v74, 32, v234
	v_add_u32_e32 v75, 64, v75
	v_cmp_lt_i32_e32 vcc, v74, v75
	s_waitcnt vmcnt(0)
	v_mul_f32_e32 v102, 0xbfb8aa3b, v102
	v_cndmask_b32_e32 v74, v234, v74, vcc
	v_lshlrev_b32_e32 v182, 2, v74
	global_load_dwordx2 v[74:75], v[186:187], off offset:96
	global_load_dwordx2 v[78:79], v[186:187], off offset:112
	global_load_dwordx2 v[82:83], v[186:187], off offset:128
	global_load_dwordx2 v[84:85], v[186:187], off offset:144
	global_load_dwordx2 v[88:89], v[186:187], off offset:160
	global_load_dwordx2 v[92:93], v[186:187], off offset:176
	global_load_dwordx2 v[94:95], v[186:187], off offset:192
	global_load_dwordx2 v[96:97], v[186:187], off offset:208
	global_load_dwordx2 v[98:99], v[186:187], off offset:224
	global_load_dwordx2 v[100:101], v[186:187], off offset:240
	ds_bpermute_b32 v181, v182, v119
	v_exp_f32_e32 v118, v102
	v_and_b32_e32 v107, 0xffff0000, v77
	v_lshlrev_b32_e32 v106, 16, v77
	v_and_b32_e32 v103, 0xffff0000, v72
	v_lshlrev_b32_e32 v102, 16, v72
	v_and_b32_e32 v105, 0xffff0000, v73
	v_lshlrev_b32_e32 v104, 16, v73
	v_and_b32_e32 v73, 0xffff0000, v76
	v_lshlrev_b32_e32 v72, 16, v76
	v_and_b32_e32 v77, 0xffff0000, v80
	v_lshlrev_b32_e32 v76, 16, v80
	v_and_b32_e32 v109, 0xffff0000, v81
	v_lshlrev_b32_e32 v108, 16, v81
	v_and_b32_e32 v81, 0xffff0000, v86
	v_lshlrev_b32_e32 v80, 16, v86
	v_and_b32_e32 v111, 0xffff0000, v87
	v_lshlrev_b32_e32 v110, 16, v87
	v_and_b32_e32 v87, 0xffff0000, v90
	v_lshlrev_b32_e32 v86, 16, v90
	v_and_b32_e32 v113, 0xffff0000, v91
	v_lshlrev_b32_e32 v112, 16, v91
	s_waitcnt lgkmcnt(0)
	v_pk_add_f32 v[90:91], v[118:119], v[180:181]
	v_and_b32_e32 v115, 0xffff0000, v70
	v_div_scale_f32 v114, s[100:101], v90, v90, 1.0
	v_rcp_f32_e32 v118, v114
	v_div_scale_f32 v119, vcc, 1.0, v90, 1.0
	v_fma_f32 v120, -v114, v118, 1.0
	v_fmac_f32_e32 v118, v120, v118
	v_mul_f32_e32 v120, v119, v118
	v_fma_f32 v121, -v114, v120, v119
	v_fmac_f32_e32 v120, v121, v118
	v_fma_f32 v114, -v114, v120, v119
	v_div_fmas_f32 v114, v114, v118, v120
	v_div_fixup_f32 v90, v114, v90, 1.0
	v_div_scale_f32 v118, s[100:101], v91, v91, v90
	v_rcp_f32_e32 v119, v118
	v_lshlrev_b32_e32 v114, 16, v70
	v_div_scale_f32 v70, vcc, v90, v91, v90
	v_fma_f32 v120, -v118, v119, 1.0
	v_fmac_f32_e32 v119, v120, v119
	v_mul_f32_e32 v120, v70, v119
	v_fma_f32 v121, -v118, v120, v70
	v_fmac_f32_e32 v120, v121, v119
	v_fma_f32 v70, -v118, v120, v70
	v_div_fmas_f32 v70, v70, v119, v120
	v_div_fixup_f32 v70, v70, v91, v90
	v_pk_fma_f32 v[36:37], v[36:37], v[70:71], v[86:87] op_sel_hi:[1,0,1]
	v_pk_fma_f32 v[38:39], v[38:39], v[70:71], v[112:113] op_sel_hi:[1,0,1]
	v_pk_fma_f32 v[52:53], v[52:53], v[70:71], v[102:103] op_sel_hi:[1,0,1]
	v_pk_fma_f32 v[54:55], v[54:55], v[70:71], v[104:105] op_sel_hi:[1,0,1]
	v_cvt_pk_bf16_f32 v36, v36, v37
	v_cvt_pk_bf16_f32 v37, v38, v39
	v_and_b32_e32 v39, 0xffff0000, v71
	v_lshlrev_b32_e32 v38, 16, v71
	v_pk_fma_f32 v[56:57], v[56:57], v[70:71], v[72:73] op_sel_hi:[1,0,1]
	v_pk_fma_f32 v[58:59], v[58:59], v[70:71], v[106:107] op_sel_hi:[1,0,1]
	v_pk_fma_f32 v[60:61], v[60:61], v[70:71], v[76:77] op_sel_hi:[1,0,1]
	v_pk_fma_f32 v[62:63], v[62:63], v[70:71], v[108:109] op_sel_hi:[1,0,1]
	v_pk_fma_f32 v[64:65], v[64:65], v[70:71], v[80:81] op_sel_hi:[1,0,1]
	v_pk_fma_f32 v[66:67], v[66:67], v[70:71], v[110:111] op_sel_hi:[1,0,1]
	v_pk_fma_f32 v[40:41], v[40:41], v[70:71], v[114:115] op_sel_hi:[1,0,1]
	v_cvt_pk_bf16_f32 v52, v52, v53
	v_cvt_pk_bf16_f32 v53, v54, v55
	v_pk_fma_f32 v[38:39], v[42:43], v[70:71], v[38:39] op_sel_hi:[1,0,1]
	v_cvt_pk_bf16_f32 v54, v56, v57
	v_cvt_pk_bf16_f32 v55, v58, v59
	v_cvt_pk_bf16_f32 v56, v60, v61
	v_cvt_pk_bf16_f32 v57, v62, v63
	v_cvt_pk_bf16_f32 v58, v64, v65
	v_cvt_pk_bf16_f32 v59, v66, v67
	global_store_dwordx2 v[68:69], v[52:53], off offset:2560
	global_store_dwordx2 v[186:187], v[54:55], off offset:16
	global_store_dwordx2 v[186:187], v[56:57], off offset:32
	global_store_dwordx2 v[186:187], v[58:59], off offset:48
	global_store_dwordx2 v[186:187], v[36:37], off offset:64
	v_cvt_pk_bf16_f32 v36, v40, v41
	v_cvt_pk_bf16_f32 v37, v38, v39
	global_store_dwordx2 v[186:187], v[36:37], off offset:80
	s_waitcnt vmcnt(15)
; __device__ __forceinline__ float bf2f(bf16 v) { return __uint_as_float(((unsigned)v) << 16); }
; __device__ __forceinline__ unsigned cvt2(float lo, float hi) { f32x2 v = {lo, hi}; return __builtin_bit_cast(unsigned, __builtin_convertvector(v, bf16x2_t)); }
; #define ATT_BAR() asm volatile("s_waitcnt lgkmcnt(0)\n\ts_barrier" ::: "memory")
; template <int MODE> __device__ __forceinline__ void attn_branch(const bf16* __restrict__ Kbase, const bf16* __restrict__ VTbase, int kt_lo, int kt_hi, int tq0, int t, int h, int q, int tid, int wave, ...
;     ...
;     ATT_BAR();
;     dma(kt_lo, 0);
;     if (kt_lo < kt_hi) { dma(kt_lo + 1, 1); asm volatile("s_waitcnt vmcnt(4)" ::: "memory"); } else asm volatile("s_waitcnt vmcnt(0)" ::: "memory");
;     ATT_BAR();
; __device__ __forceinline__ void ph_nsa_main(const bf16* __restrict__ NQ, const bf16* __restrict__ KS, const bf16* __restrict__ KW, const bf16* __restrict__ VST, const bf16* __restrict__ VWT, ...
;     ...
;               for (int gq = 0; gq < 4; ++gq) { const int d = 32 * dt + 8 * gq + 4 * h;
;                   const u32x2 ocv = *(const u32x2*)(mix + m * D_MODEL + 1280 + head * 128 + d);
;                   u32x2 w; w.x = cvt2(O[dt][4 * gq] * sc + bf2f((bf16)(ocv.x & 0xffff)), O[dt][4 * gq + 1] * sc + bf2f((bf16)(ocv.x >> 16)));
;                   w.y = cvt2(O[dt][4 * gq + 2] * sc + bf2f((bf16)(ocv.y & 0xffff)), O[dt][4 * gq + 3] * sc + bf2f((bf16)(ocv.y >> 16)));
;                   *(u32x2*)(mix + m * D_MODEL + 1280 + head * 128 + d) = w; }
; #pragma unroll
;           for (int dt = 0; dt < 4; ++dt)
; #pragma unroll
;               for (int i = 0; i < 16; ++i) O[dt][i] = 0.f; }
;         lsum = 0.f;
;         { const int lo = t0 - 512 > 0 ? (t0 - 512) >> 6 : 0;
;           attn_branch<1>(KW + (size_t)(b * 2 + g) * SEQ * 128, VWT + (size_t)(b * 2 + g) * 128 * SEQ, lo, (t0 + 255) >> 6, tq0, t, h, q, tid, wave, 0ull, qf, O, lsum); }
	v_and_b32_e32 v37, 0xffff0000, v74
	v_lshlrev_b32_e32 v36, 16, v74
	v_and_b32_e32 v39, 0xffff0000, v75
	v_lshlrev_b32_e32 v38, 16, v75
	v_pk_fma_f32 v[36:37], v[44:45], v[70:71], v[36:37] op_sel_hi:[1,0,1]
	v_pk_fma_f32 v[38:39], v[46:47], v[70:71], v[38:39] op_sel_hi:[1,0,1]
	v_cvt_pk_bf16_f32 v36, v36, v37
	v_cvt_pk_bf16_f32 v37, v38, v39
	global_store_dwordx2 v[186:187], v[36:37], off offset:96
	s_waitcnt vmcnt(15)
	v_and_b32_e32 v37, 0xffff0000, v78
	v_lshlrev_b32_e32 v36, 16, v78
	v_and_b32_e32 v39, 0xffff0000, v79
	v_lshlrev_b32_e32 v38, 16, v79
	v_pk_fma_f32 v[36:37], v[48:49], v[70:71], v[36:37] op_sel_hi:[1,0,1]
	v_pk_fma_f32 v[38:39], v[50:51], v[70:71], v[38:39] op_sel_hi:[1,0,1]
	v_cvt_pk_bf16_f32 v36, v36, v37
	v_cvt_pk_bf16_f32 v37, v38, v39
	global_store_dwordx2 v[186:187], v[36:37], off offset:112
	s_waitcnt vmcnt(15)
	v_and_b32_e32 v37, 0xffff0000, v82
	v_lshlrev_b32_e32 v36, 16, v82
	v_pk_fma_f32 v[20:21], v[20:21], v[70:71], v[36:37] op_sel_hi:[1,0,1]
	v_and_b32_e32 v37, 0xffff0000, v83
	v_lshlrev_b32_e32 v36, 16, v83
	v_pk_fma_f32 v[22:23], v[22:23], v[70:71], v[36:37] op_sel_hi:[1,0,1]
	v_cvt_pk_bf16_f32 v20, v20, v21
	v_cvt_pk_bf16_f32 v21, v22, v23
	global_store_dwordx2 v[186:187], v[20:21], off offset:128
	s_waitcnt vmcnt(15)
	v_and_b32_e32 v21, 0xffff0000, v84
	v_lshlrev_b32_e32 v20, 16, v84
	v_and_b32_e32 v23, 0xffff0000, v85
	v_lshlrev_b32_e32 v22, 16, v85
	v_pk_fma_f32 v[20:21], v[24:25], v[70:71], v[20:21] op_sel_hi:[1,0,1]
	v_pk_fma_f32 v[22:23], v[26:27], v[70:71], v[22:23] op_sel_hi:[1,0,1]
	v_cvt_pk_bf16_f32 v20, v20, v21
	v_cvt_pk_bf16_f32 v21, v22, v23
	global_store_dwordx2 v[186:187], v[20:21], off offset:144
	s_waitcnt vmcnt(15)
	v_and_b32_e32 v21, 0xffff0000, v88
	v_lshlrev_b32_e32 v20, 16, v88
	v_and_b32_e32 v23, 0xffff0000, v89
	v_lshlrev_b32_e32 v22, 16, v89
	v_pk_fma_f32 v[20:21], v[28:29], v[70:71], v[20:21] op_sel_hi:[1,0,1]
	v_pk_fma_f32 v[22:23], v[30:31], v[70:71], v[22:23] op_sel_hi:[1,0,1]
	v_cvt_pk_bf16_f32 v20, v20, v21
	v_cvt_pk_bf16_f32 v21, v22, v23
	global_store_dwordx2 v[186:187], v[20:21], off offset:160
	s_waitcnt vmcnt(15)
	v_and_b32_e32 v21, 0xffff0000, v92
	v_lshlrev_b32_e32 v20, 16, v92
	v_and_b32_e32 v23, 0xffff0000, v93
	v_lshlrev_b32_e32 v22, 16, v93
	v_pk_fma_f32 v[20:21], v[32:33], v[70:71], v[20:21] op_sel_hi:[1,0,1]
	v_pk_fma_f32 v[22:23], v[34:35], v[70:71], v[22:23] op_sel_hi:[1,0,1]
	v_cvt_pk_bf16_f32 v20, v20, v21
	v_cvt_pk_bf16_f32 v21, v22, v23
	global_store_dwordx2 v[186:187], v[20:21], off offset:176
	s_waitcnt vmcnt(15)
	v_and_b32_e32 v21, 0xffff0000, v94
	v_lshlrev_b32_e32 v20, 16, v94
	v_pk_fma_f32 v[4:5], v[4:5], v[70:71], v[20:21] op_sel_hi:[1,0,1]
	v_and_b32_e32 v21, 0xffff0000, v95
	v_lshlrev_b32_e32 v20, 16, v95
	v_pk_fma_f32 v[6:7], v[6:7], v[70:71], v[20:21] op_sel_hi:[1,0,1]
	s_lshr_b32 s100, s94, 6
	v_cvt_pk_bf16_f32 v4, v4, v5
	v_cvt_pk_bf16_f32 v5, v6, v7
	s_or_b32 s20, s100, 3
	global_store_dwordx2 v[186:187], v[4:5], off offset:192
	s_waitcnt vmcnt(15)
	v_and_b32_e32 v5, 0xffff0000, v96
	v_lshlrev_b32_e32 v4, 16, v96
	v_and_b32_e32 v7, 0xffff0000, v97
	v_lshlrev_b32_e32 v6, 16, v97
	v_pk_fma_f32 v[4:5], v[8:9], v[70:71], v[4:5] op_sel_hi:[1,0,1]
	v_pk_fma_f32 v[6:7], v[10:11], v[70:71], v[6:7] op_sel_hi:[1,0,1]
	v_cvt_pk_bf16_f32 v4, v4, v5
	v_cvt_pk_bf16_f32 v5, v6, v7
	global_store_dwordx2 v[186:187], v[4:5], off offset:208
	s_waitcnt vmcnt(15)
	v_and_b32_e32 v5, 0xffff0000, v98
	v_lshlrev_b32_e32 v4, 16, v98
	v_and_b32_e32 v7, 0xffff0000, v99
	v_lshlrev_b32_e32 v6, 16, v99
	v_pk_fma_f32 v[4:5], v[12:13], v[70:71], v[4:5] op_sel_hi:[1,0,1]
	v_pk_fma_f32 v[6:7], v[14:15], v[70:71], v[6:7] op_sel_hi:[1,0,1]
	v_cvt_pk_bf16_f32 v4, v4, v5
	v_cvt_pk_bf16_f32 v5, v6, v7
	global_store_dwordx2 v[186:187], v[4:5], off offset:224
	s_waitcnt vmcnt(15)
	v_and_b32_e32 v5, 0xffff0000, v100
	v_lshlrev_b32_e32 v4, 16, v100
	v_and_b32_e32 v7, 0xffff0000, v101
	v_lshlrev_b32_e32 v6, 16, v101
	v_pk_fma_f32 v[4:5], v[16:17], v[70:71], v[4:5] op_sel_hi:[1,0,1]
	v_pk_fma_f32 v[6:7], v[18:19], v[70:71], v[6:7] op_sel_hi:[1,0,1]
	v_cvt_pk_bf16_f32 v4, v4, v5
	v_cvt_pk_bf16_f32 v5, v6, v7
	global_store_dwordx2 v[186:187], v[4:5], off offset:240
	s_waitcnt lgkmcnt(0)
	s_barrier
	s_cmp_ge_i32 s16, s20
	s_mov_b64 s[18:19], -1
	s_cbranch_scc0 .LBB0_1849
	s_waitcnt vmcnt(0)
	s_mov_b64 s[18:19], 0
